# out-projection epilogue de-serialised: 16 x loads in flight, counted vmcnt, 32-bit offsets
# baseline (speedup 1.0000x reference)
.LBB0_728:
	s_lshl_b32 s56, s45, 8
	s_or_b32 s56, s56, s68
	s_lshl_b32 s0, s44, 8
	v_readlane_b32 s44, v253, 0
	v_readlane_b32 s45, v253, 1
	v_readlane_b32 s46, v253, 2
	v_readlane_b32 s47, v253, 3
	v_and_b32_e32 v128, 15, v174
	v_lshrrev_b32_e32 v129, 4, v174
	v_or_b32_e32 v128, s91, v128
	s_cmp_lt_u32 s0, 0x8000
	s_cselect_b32 s48, s44, s46
	s_cselect_b32 s49, s45, s47
	s_cselect_b32 s54, 0, 0x8000
	s_sub_u32 s54, s0, s54
	s_lshl_b32 s54, s54, 12
	s_add_u32 s48, s48, s54
	s_addc_u32 s49, s49, 0
	s_lshl_b32 s55, s56, 2
	s_add_u32 s48, s48, s55
	s_addc_u32 s49, s49, 0
	s_lshl_b32 s55, s0, 11
	s_add_u32 s50, s10, s55
	s_addc_u32 s51, s11, 0
	s_lshl_b32 s55, s56, 1
	s_add_u32 s50, s50, s55
	s_addc_u32 s51, s51, 0
	s_mov_b32 s52, 0x3f9837f0
	v_lshlrev_b32_e32 v130, 12, v128
	v_lshlrev_b32_e32 v131, 11, v128
	v_lshl_add_u32 v130, v129, 4, v130
	v_lshl_add_u32 v131, v129, 3, v131
	global_load_dwordx4 v[132:135], v130, s[48:49]
	global_load_dwordx4 v[136:139], v130, s[48:49] offset:64
	global_load_dwordx4 v[140:143], v130, s[48:49] offset:512
	global_load_dwordx4 v[148:151], v130, s[48:49] offset:576
	v_add_u32_e32 v130, 0x10000, v130
	global_load_dwordx4 v[152:155], v130, s[48:49]
	global_load_dwordx4 v[156:159], v130, s[48:49] offset:64
	global_load_dwordx4 v[180:183], v130, s[48:49] offset:512
	global_load_dwordx4 v[184:187], v130, s[48:49] offset:576
	v_add_u32_e32 v130, 0x10000, v130
	global_load_dwordx4 v[188:191], v130, s[48:49]
	global_load_dwordx4 v[192:195], v130, s[48:49] offset:64
	global_load_dwordx4 v[196:199], v130, s[48:49] offset:512
	global_load_dwordx4 v[200:203], v130, s[48:49] offset:576
	v_add_u32_e32 v130, 0x10000, v130
	global_load_dwordx4 v[204:207], v130, s[48:49]
	global_load_dwordx4 v[208:211], v130, s[48:49] offset:64
	global_load_dwordx4 v[232:235], v130, s[48:49] offset:512
	global_load_dwordx4 v[236:239], v130, s[48:49] offset:576
	v_add_u32_e32 v130, 0x50000, v130
	s_waitcnt vmcnt(15)
	v_pk_fma_f32 v[124:125], v[132:133], s[52:53], v[124:125] op_sel_hi:[1,0,1]
	v_pk_fma_f32 v[126:127], v[134:135], s[52:53], v[126:127] op_sel_hi:[1,0,1]
	v_cvt_pk_bf16_f32 v124, v124, v125
	v_cvt_pk_bf16_f32 v125, v126, v127
	global_store_dwordx2 v131, v[124:125], s[50:51]
	s_waitcnt vmcnt(15)
	v_pk_fma_f32 v[120:121], v[136:137], s[52:53], v[120:121] op_sel_hi:[1,0,1]
	v_pk_fma_f32 v[122:123], v[138:139], s[52:53], v[122:123] op_sel_hi:[1,0,1]
	v_cvt_pk_bf16_f32 v120, v120, v121
	v_cvt_pk_bf16_f32 v121, v122, v123
	global_store_dwordx2 v131, v[120:121], s[50:51] offset:32
	s_waitcnt vmcnt(15)
	v_pk_fma_f32 v[116:117], v[140:141], s[52:53], v[116:117] op_sel_hi:[1,0,1]
	v_pk_fma_f32 v[118:119], v[142:143], s[52:53], v[118:119] op_sel_hi:[1,0,1]
	v_cvt_pk_bf16_f32 v116, v116, v117
	v_cvt_pk_bf16_f32 v117, v118, v119
	global_store_dwordx2 v131, v[116:117], s[50:51] offset:256
	s_waitcnt vmcnt(15)
	v_pk_fma_f32 v[108:109], v[148:149], s[52:53], v[108:109] op_sel_hi:[1,0,1]
	v_pk_fma_f32 v[110:111], v[150:151], s[52:53], v[110:111] op_sel_hi:[1,0,1]
	v_cvt_pk_bf16_f32 v108, v108, v109
	v_cvt_pk_bf16_f32 v109, v110, v111
	global_store_dwordx2 v131, v[108:109], s[50:51] offset:288
	v_add_u32_e32 v131, 0x8000, v131
	global_load_dwordx4 v[132:135], v130, s[48:49]
	global_load_dwordx4 v[136:139], v130, s[48:49] offset:64
	global_load_dwordx4 v[140:143], v130, s[48:49] offset:512
	global_load_dwordx4 v[148:151], v130, s[48:49] offset:576
	v_add_u32_e32 v130, 0x10000, v130
	s_waitcnt vmcnt(19)
	v_pk_fma_f32 v[112:113], v[152:153], s[52:53], v[112:113] op_sel_hi:[1,0,1]
	v_pk_fma_f32 v[114:115], v[154:155], s[52:53], v[114:115] op_sel_hi:[1,0,1]
	v_cvt_pk_bf16_f32 v112, v112, v113
	v_cvt_pk_bf16_f32 v113, v114, v115
	global_store_dwordx2 v131, v[112:113], s[50:51]
	s_waitcnt vmcnt(19)
	v_pk_fma_f32 v[104:105], v[156:157], s[52:53], v[104:105] op_sel_hi:[1,0,1]
	v_pk_fma_f32 v[106:107], v[158:159], s[52:53], v[106:107] op_sel_hi:[1,0,1]
	v_cvt_pk_bf16_f32 v104, v104, v105
	v_cvt_pk_bf16_f32 v105, v106, v107
	global_store_dwordx2 v131, v[104:105], s[50:51] offset:32
	s_waitcnt vmcnt(19)
	v_pk_fma_f32 v[100:101], v[180:181], s[52:53], v[100:101] op_sel_hi:[1,0,1]
	v_pk_fma_f32 v[102:103], v[182:183], s[52:53], v[102:103] op_sel_hi:[1,0,1]
	v_cvt_pk_bf16_f32 v100, v100, v101
	v_cvt_pk_bf16_f32 v101, v102, v103
	global_store_dwordx2 v131, v[100:101], s[50:51] offset:256
	s_waitcnt vmcnt(19)
	v_pk_fma_f32 v[92:93], v[184:185], s[52:53], v[92:93] op_sel_hi:[1,0,1]
	v_pk_fma_f32 v[94:95], v[186:187], s[52:53], v[94:95] op_sel_hi:[1,0,1]
	v_cvt_pk_bf16_f32 v92, v92, v93
	v_cvt_pk_bf16_f32 v93, v94, v95
	global_store_dwordx2 v131, v[92:93], s[50:51] offset:288
	v_add_u32_e32 v131, 0x8000, v131
	global_load_dwordx4 v[152:155], v130, s[48:49]
	global_load_dwordx4 v[156:159], v130, s[48:49] offset:64
	global_load_dwordx4 v[180:183], v130, s[48:49] offset:512
	global_load_dwordx4 v[184:187], v130, s[48:49] offset:576
	v_add_u32_e32 v130, 0x10000, v130
	s_waitcnt vmcnt(23)
	v_pk_fma_f32 v[96:97], v[188:189], s[52:53], v[96:97] op_sel_hi:[1,0,1]
	v_pk_fma_f32 v[98:99], v[190:191], s[52:53], v[98:99] op_sel_hi:[1,0,1]
	v_cvt_pk_bf16_f32 v96, v96, v97
	v_cvt_pk_bf16_f32 v97, v98, v99
	global_store_dwordx2 v131, v[96:97], s[50:51]
	s_waitcnt vmcnt(23)
	v_pk_fma_f32 v[88:89], v[192:193], s[52:53], v[88:89] op_sel_hi:[1,0,1]
	v_pk_fma_f32 v[90:91], v[194:195], s[52:53], v[90:91] op_sel_hi:[1,0,1]
	v_cvt_pk_bf16_f32 v88, v88, v89
	v_cvt_pk_bf16_f32 v89, v90, v91
	global_store_dwordx2 v131, v[88:89], s[50:51] offset:32
	s_waitcnt vmcnt(23)
	v_pk_fma_f32 v[84:85], v[196:197], s[52:53], v[84:85] op_sel_hi:[1,0,1]
	v_pk_fma_f32 v[86:87], v[198:199], s[52:53], v[86:87] op_sel_hi:[1,0,1]
	v_cvt_pk_bf16_f32 v84, v84, v85
	v_cvt_pk_bf16_f32 v85, v86, v87
	global_store_dwordx2 v131, v[84:85], s[50:51] offset:256
	s_waitcnt vmcnt(23)
	v_pk_fma_f32 v[76:77], v[200:201], s[52:53], v[76:77] op_sel_hi:[1,0,1]
	v_pk_fma_f32 v[78:79], v[202:203], s[52:53], v[78:79] op_sel_hi:[1,0,1]
	v_cvt_pk_bf16_f32 v76, v76, v77
	v_cvt_pk_bf16_f32 v77, v78, v79
	global_store_dwordx2 v131, v[76:77], s[50:51] offset:288
	v_add_u32_e32 v131, 0x8000, v131
	global_load_dwordx4 v[188:191], v130, s[48:49]
	global_load_dwordx4 v[192:195], v130, s[48:49] offset:64
	global_load_dwordx4 v[196:199], v130, s[48:49] offset:512
	global_load_dwordx4 v[200:203], v130, s[48:49] offset:576
	v_add_u32_e32 v130, 0x10000, v130
	s_waitcnt vmcnt(27)
	v_pk_fma_f32 v[80:81], v[204:205], s[52:53], v[80:81] op_sel_hi:[1,0,1]
	v_pk_fma_f32 v[82:83], v[206:207], s[52:53], v[82:83] op_sel_hi:[1,0,1]
	v_cvt_pk_bf16_f32 v80, v80, v81
	v_cvt_pk_bf16_f32 v81, v82, v83
	global_store_dwordx2 v131, v[80:81], s[50:51]
	s_waitcnt vmcnt(27)
	v_pk_fma_f32 v[72:73], v[208:209], s[52:53], v[72:73] op_sel_hi:[1,0,1]
	v_pk_fma_f32 v[74:75], v[210:211], s[52:53], v[74:75] op_sel_hi:[1,0,1]
	v_cvt_pk_bf16_f32 v72, v72, v73
	v_cvt_pk_bf16_f32 v73, v74, v75
	global_store_dwordx2 v131, v[72:73], s[50:51] offset:32
	s_waitcnt vmcnt(27)
	v_pk_fma_f32 v[68:69], v[232:233], s[52:53], v[68:69] op_sel_hi:[1,0,1]
	v_pk_fma_f32 v[70:71], v[234:235], s[52:53], v[70:71] op_sel_hi:[1,0,1]
	v_cvt_pk_bf16_f32 v68, v68, v69
	v_cvt_pk_bf16_f32 v69, v70, v71
	global_store_dwordx2 v131, v[68:69], s[50:51] offset:256
	s_waitcnt vmcnt(27)
	v_pk_fma_f32 v[64:65], v[236:237], s[52:53], v[64:65] op_sel_hi:[1,0,1]
	v_pk_fma_f32 v[66:67], v[238:239], s[52:53], v[66:67] op_sel_hi:[1,0,1]
	v_cvt_pk_bf16_f32 v64, v64, v65
	v_cvt_pk_bf16_f32 v65, v66, v67
	global_store_dwordx2 v131, v[64:65], s[50:51] offset:288
	v_add_u32_e32 v131, 0x28000, v131
	global_load_dwordx4 v[204:207], v130, s[48:49]
	global_load_dwordx4 v[208:211], v130, s[48:49] offset:64
	global_load_dwordx4 v[232:235], v130, s[48:49] offset:512
	global_load_dwordx4 v[236:239], v130, s[48:49] offset:576
	s_waitcnt vmcnt(27)
	v_pk_fma_f32 v[60:61], v[132:133], s[52:53], v[60:61] op_sel_hi:[1,0,1]
	v_pk_fma_f32 v[62:63], v[134:135], s[52:53], v[62:63] op_sel_hi:[1,0,1]
	v_cvt_pk_bf16_f32 v60, v60, v61
	v_cvt_pk_bf16_f32 v61, v62, v63
	global_store_dwordx2 v131, v[60:61], s[50:51]
	s_waitcnt vmcnt(27)
	v_pk_fma_f32 v[56:57], v[136:137], s[52:53], v[56:57] op_sel_hi:[1,0,1]
	v_pk_fma_f32 v[58:59], v[138:139], s[52:53], v[58:59] op_sel_hi:[1,0,1]
	v_cvt_pk_bf16_f32 v56, v56, v57
	v_cvt_pk_bf16_f32 v57, v58, v59
	global_store_dwordx2 v131, v[56:57], s[50:51] offset:32
	s_waitcnt vmcnt(27)
	v_pk_fma_f32 v[52:53], v[140:141], s[52:53], v[52:53] op_sel_hi:[1,0,1]
	v_pk_fma_f32 v[54:55], v[142:143], s[52:53], v[54:55] op_sel_hi:[1,0,1]
	v_cvt_pk_bf16_f32 v52, v52, v53
	v_cvt_pk_bf16_f32 v53, v54, v55
	global_store_dwordx2 v131, v[52:53], s[50:51] offset:256
	s_waitcnt vmcnt(27)
	v_pk_fma_f32 v[44:45], v[148:149], s[52:53], v[44:45] op_sel_hi:[1,0,1]
	v_pk_fma_f32 v[46:47], v[150:151], s[52:53], v[46:47] op_sel_hi:[1,0,1]
	v_cvt_pk_bf16_f32 v44, v44, v45
	v_cvt_pk_bf16_f32 v45, v46, v47
	global_store_dwordx2 v131, v[44:45], s[50:51] offset:288
	v_add_u32_e32 v131, 0x8000, v131
	s_waitcnt vmcnt(23)
	v_pk_fma_f32 v[48:49], v[152:153], s[52:53], v[48:49] op_sel_hi:[1,0,1]
	v_pk_fma_f32 v[50:51], v[154:155], s[52:53], v[50:51] op_sel_hi:[1,0,1]
	v_cvt_pk_bf16_f32 v48, v48, v49
	v_cvt_pk_bf16_f32 v49, v50, v51
	global_store_dwordx2 v131, v[48:49], s[50:51]
	s_waitcnt vmcnt(23)
	v_pk_fma_f32 v[40:41], v[156:157], s[52:53], v[40:41] op_sel_hi:[1,0,1]
	v_pk_fma_f32 v[42:43], v[158:159], s[52:53], v[42:43] op_sel_hi:[1,0,1]
	v_cvt_pk_bf16_f32 v40, v40, v41
	v_cvt_pk_bf16_f32 v41, v42, v43
	global_store_dwordx2 v131, v[40:41], s[50:51] offset:32
	s_waitcnt vmcnt(23)
	v_pk_fma_f32 v[36:37], v[180:181], s[52:53], v[36:37] op_sel_hi:[1,0,1]
	v_pk_fma_f32 v[38:39], v[182:183], s[52:53], v[38:39] op_sel_hi:[1,0,1]
	v_cvt_pk_bf16_f32 v36, v36, v37
	v_cvt_pk_bf16_f32 v37, v38, v39
	global_store_dwordx2 v131, v[36:37], s[50:51] offset:256
	s_waitcnt vmcnt(23)
	v_pk_fma_f32 v[28:29], v[184:185], s[52:53], v[28:29] op_sel_hi:[1,0,1]
	v_pk_fma_f32 v[30:31], v[186:187], s[52:53], v[30:31] op_sel_hi:[1,0,1]
	v_cvt_pk_bf16_f32 v28, v28, v29
	v_cvt_pk_bf16_f32 v29, v30, v31
	global_store_dwordx2 v131, v[28:29], s[50:51] offset:288
	v_add_u32_e32 v131, 0x8000, v131
	s_waitcnt vmcnt(19)
	v_pk_fma_f32 v[32:33], v[188:189], s[52:53], v[32:33] op_sel_hi:[1,0,1]
	v_pk_fma_f32 v[34:35], v[190:191], s[52:53], v[34:35] op_sel_hi:[1,0,1]
	v_cvt_pk_bf16_f32 v32, v32, v33
	v_cvt_pk_bf16_f32 v33, v34, v35
	global_store_dwordx2 v131, v[32:33], s[50:51]
	s_waitcnt vmcnt(19)
	v_pk_fma_f32 v[24:25], v[192:193], s[52:53], v[24:25] op_sel_hi:[1,0,1]
	v_pk_fma_f32 v[26:27], v[194:195], s[52:53], v[26:27] op_sel_hi:[1,0,1]
	v_cvt_pk_bf16_f32 v24, v24, v25
	v_cvt_pk_bf16_f32 v25, v26, v27
	global_store_dwordx2 v131, v[24:25], s[50:51] offset:32
	s_waitcnt vmcnt(19)
	v_pk_fma_f32 v[20:21], v[196:197], s[52:53], v[20:21] op_sel_hi:[1,0,1]
	v_pk_fma_f32 v[22:23], v[198:199], s[52:53], v[22:23] op_sel_hi:[1,0,1]
	v_cvt_pk_bf16_f32 v20, v20, v21
	v_cvt_pk_bf16_f32 v21, v22, v23
	global_store_dwordx2 v131, v[20:21], s[50:51] offset:256
	s_waitcnt vmcnt(19)
	v_pk_fma_f32 v[12:13], v[200:201], s[52:53], v[12:13] op_sel_hi:[1,0,1]
	v_pk_fma_f32 v[14:15], v[202:203], s[52:53], v[14:15] op_sel_hi:[1,0,1]
	v_cvt_pk_bf16_f32 v12, v12, v13
	v_cvt_pk_bf16_f32 v13, v14, v15
	global_store_dwordx2 v131, v[12:13], s[50:51] offset:288
	v_add_u32_e32 v131, 0x8000, v131
	s_waitcnt vmcnt(15)
	v_pk_fma_f32 v[16:17], v[204:205], s[52:53], v[16:17] op_sel_hi:[1,0,1]
	v_pk_fma_f32 v[18:19], v[206:207], s[52:53], v[18:19] op_sel_hi:[1,0,1]
	v_cvt_pk_bf16_f32 v16, v16, v17
	v_cvt_pk_bf16_f32 v17, v18, v19
	global_store_dwordx2 v131, v[16:17], s[50:51]
	s_waitcnt vmcnt(15)
	v_pk_fma_f32 v[8:9], v[208:209], s[52:53], v[8:9] op_sel_hi:[1,0,1]
	v_pk_fma_f32 v[10:11], v[210:211], s[52:53], v[10:11] op_sel_hi:[1,0,1]
	v_cvt_pk_bf16_f32 v8, v8, v9
	v_cvt_pk_bf16_f32 v9, v10, v11
	global_store_dwordx2 v131, v[8:9], s[50:51] offset:32
	s_waitcnt vmcnt(15)
	v_pk_fma_f32 v[4:5], v[232:233], s[52:53], v[4:5] op_sel_hi:[1,0,1]
	v_pk_fma_f32 v[6:7], v[234:235], s[52:53], v[6:7] op_sel_hi:[1,0,1]
	v_cvt_pk_bf16_f32 v4, v4, v5
	v_cvt_pk_bf16_f32 v5, v6, v7
	global_store_dwordx2 v131, v[4:5], s[50:51] offset:256
	s_waitcnt vmcnt(15)
	v_pk_fma_f32 v[0:1], v[236:237], s[52:53], v[0:1] op_sel_hi:[1,0,1]
	v_pk_fma_f32 v[2:3], v[238:239], s[52:53], v[2:3] op_sel_hi:[1,0,1]
	v_cvt_pk_bf16_f32 v0, v0, v1
	v_cvt_pk_bf16_f32 v1, v2, v3
	global_store_dwordx2 v131, v[0:1], s[50:51] offset:288
	s_andn2_b64 vcc, exec, s[16:17]
	s_mov_b64 s[16:17], -1
	s_cbranch_vccnz .LBB0_717
	s_andn2_b64 vcc, exec, s[4:5]
	s_cbranch_vccnz .LBB0_716
	s_barrier
	s_branch .LBB0_716

.LBB0_1020:
	s_or_b64 exec, exec, s[48:49]
	v_add_u32_sdwa v78, v77, v76 dst_sel:DWORD dst_unused:UNUSED_PAD src0_sel:WORD_0 src1_sel:DWORD
	v_cndmask_b32_e64 v76, 0, 1, s[42:43]
	v_add_u32_sdwa v79, v77, v76 dst_sel:DWORD dst_unused:UNUSED_PAD src0_sel:WORD_1 src1_sel:DWORD
	s_nop 0
	v_cmp_lt_u32_e64 s[42:43], v79, v73
	v_min_u32_e32 v76, v79, v73
	s_and_b64 s[42:43], s[38:39], s[42:43]
	v_add_u32_e32 v76, v76, v78
	v_cndmask_b32_e64 v60, 0, 1, s[44:45]
	s_or_b64 s[44:45], s[44:45], s[42:43]
	v_cmp_gt_u32_e64 s[42:43], s50, v76
	s_and_b64 s[42:43], s[44:45], s[42:43]
	s_and_saveexec_b64 s[44:45], s[42:43]
	s_cbranch_execz .LBB0_1022
	v_mov_b32_e32 v77, 0
	v_lshlrev_b64 v[90:91], 2, v[76:77]
	v_or_b32_e32 v89, 1, v81
	v_lshl_add_u64 v[92:93], s[70:71], 0, v[90:91]
	v_lshl_add_u64 v[90:91], s[72:73], 0, v[90:91]
	global_store_dword v[92:93], v89, off
	global_store_dword v[90:91], v61, off
